# context attention items also off the latent scans' CU-partner workgroups (taken by workgroups 384..511)
# speedup vs baseline: 1.0199x; 1.0014x over previous
.LBB0_247:
	v_readlane_b32 s2, v224, 3
	s_mov_b32 s67, 0x8000
	s_nop 0
	s_cmpk_lt_u32 s2, 0x80
	s_cbranch_scc1 .LBB0_272
	v_readlane_b32 s2, v224, 34
	v_readlane_b32 s3, v224, 35
	s_load_dwordx4 s[48:51], s[2:3], 0x170
	s_load_dwordx8 s[40:47], s[2:3], 0x150
	s_lshl_b32 s16, s28, 3
	v_readlane_b32 s6, v225, 58
	v_readlane_b32 s7, v225, 59
	s_waitcnt lgkmcnt(0)
	s_add_u32 s8, s48, 0x1040
	s_addc_u32 s9, s49, 0
	s_add_u32 s56, s50, 48
	s_addc_u32 s57, s51, 0
	s_add_u32 s12, s40, 0x1040
	s_addc_u32 s13, s41, 0
	v_readlane_b32 s58, v224, 3
	s_nop 0
	s_add_i32 s100, s58, 0xffffff00
	s_cmpk_gt_u32 s58, 0xff
	s_cselect_b32 s58, s100, s58
	s_branch .LBB0_250
